# grid-sync site also uses the hierarchical per-XCC barrier (XCD leader writeback, flag fan-out, invalidate before polling)
# speedup vs baseline: 1.0401x; 1.0001x over previous
; __global__ void __launch_bounds__(NTHREADS, 2) mega(Params p) {
;     ...
;     grid.sync();
.LBB0_130:
	s_or_b64 exec, exec, s[0:1]
	v_lshrrev_b32_e32 v1, 20, v0
	v_lshrrev_b32_e32 v0, 10, v0
	v_or_b32_e32 v0, v0, v1
	s_movk_i32 s0, 0x3ff
	v_and_or_b32 v0, v0, s0, v220
	v_cmp_eq_u32_e32 vcc, 0, v0
	s_waitcnt vmcnt(0) lgkmcnt(0)
	s_barrier
	s_add_i32 s98, s98, 1
	s_and_saveexec_b64 s[0:1], vcc
	s_xor_b64 s[0:1], exec, s[0:1]
	s_cbranch_execz .LBB0_140
	s_add_u32 s10, s88, 0x9000
	s_addc_u32 s11, s89, 0
	s_cmp_lg_u32 s100, 0
	s_cbranch_scc1 .Lxb_have_g
	s_add_u32 s8, s88, 0x1400
	s_addc_u32 s9, s89, 0
